# rg_conv: four serialized tap loads merged into one wait per iteration (predicated XR loads into zeroed buffers)
# speedup vs baseline: 1.0045x; 1.0045x over previous
; __device__ __forceinline__ unsigned pk2(float lo, float hi) { f32x2_pk v = {lo, hi}; bf16x2_pk b = __builtin_convertvector(v, bf16x2_pk); return __builtin_bit_cast(unsigned, b); }
; __device__ __forceinline__ void rg_conv_phase(const bf16_t* XR, bf16_t* XCV, const float* cw, const float* cb, int gtid, int ngt) {
;     for (int it = gtid; it < MT * 160; it += ngt) { const int m = it / 160, c8 = (it % 160) * 8;
;         int t, L; if (m < ML) { t = m & 2047; L = SEQ; } else { t = (m - ML) & 255; L = CTX; }
;         float o[8];
; #pragma unroll
;         for (int e = 0; e < 8; ++e) o[e] = cb[c8 + e];
; #pragma unroll
;         for (int k = 0; k < 4; ++k) { const int tt = t + k - 2; if (tt < 0 || tt >= L) continue;
;             const u32x4 w = *(const u32x4*)(XR + (size_t)(m + k - 2) * DRNN + c8); const float* wk = cw + k * DRNN + c8;
;             o[0] += wk[0] * bflo(w.x); o[1] += wk[1] * bfhi(w.x); o[2] += wk[2] * bflo(w.y); o[3] += wk[3] * bfhi(w.y); o[4] += wk[4] * bflo(w.z); o[5] += wk[5] * bfhi(w.z); o[6] += wk[6] * bflo(w.w); o[7] += wk[7] * bfhi(w.w); }
;         u32x4 r; r.x = pk2(o[0], o[1]); r.y = pk2(o[2], o[3]); r.z = pk2(o[4], o[5]); r.w = pk2(o[6], o[7]);
;         *(u32x4*)(XCV + (size_t)m * DRNN + c8) = r; }
.LBB0_818:
	v_mul_hi_i32 v0, v9, s43
	v_lshrrev_b32_e32 v1, 31, v0
	v_ashrrev_i32_e32 v0, 6, v0
	v_add_u32_e32 v16, v0, v1
	s_movk_i32 s3, 0xfb00
	v_mad_u64_u32 v[10:11], s[6:7], v16, s3, v[8:9]
	v_ashrrev_i32_e32 v11, 31, v10
	v_lshlrev_b64 v[12:13], 2, v[10:11]
	v_lshl_add_u64 v[4:5], s[14:15], 0, v[12:13]
	global_load_dwordx4 v[0:3], v[4:5], off offset:16
	s_nop 0
	global_load_dwordx4 v[4:7], v[4:5], off
	s_mov_b32 s3, 0x500000
	v_cmp_gt_i32_e32 vcc, s3, v9
	v_mov_b32_e32 v14, 0x7ff
	v_mov_b32_e32 v15, 0x802
	v_cndmask_b32_e32 v14, v216, v14, vcc
	v_and_b32_e32 v17, v14, v16
	v_bfrev_b32_e32 v14, 4.0
	v_cndmask_b32_e32 v18, v14, v15, vcc
	v_cmp_lt_u32_e32 vcc, 1, v17
	v_cmp_lt_u32_e64 s[6:7], v17, v18
	v_lshl_add_u64 v[14:15], v[10:11], 1, s[8:9]
	v_lshl_add_u64 v[12:13], s[12:13], 0, v[12:13]
	v_mov_b64_e32 v[34:35], 0
	v_mov_b64_e32 v[36:37], 0
	v_mov_b64_e32 v[38:39], 0
	v_mov_b64_e32 v[40:41], 0
	v_mov_b64_e32 v[42:43], 0
	v_mov_b64_e32 v[44:45], 0
	v_mov_b64_e32 v[46:47], 0
	v_mov_b64_e32 v[48:49], 0
	s_movk_i32 s3, 0xa00
	s_and_b64 s[20:21], vcc, s[6:7]
	s_and_saveexec_b64 s[6:7], s[20:21]
	v_add_u32_e32 v19, -2, v16
	v_mad_i64_i32 v[20:21], s[20:21], v19, s3, v[14:15]
	global_load_dwordx4 v[34:37], v[20:21], off
	s_or_b64 exec, exec, s[6:7]
	v_add_u32_e32 v19, 1, v17
	v_cmp_ne_u32_e32 vcc, 0, v17
	v_cmp_lt_u32_e64 s[6:7], v19, v18
	s_and_b64 s[20:21], vcc, s[6:7]
	s_and_saveexec_b64 s[6:7], s[20:21]
	v_add_u32_e32 v19, -1, v16
	v_mad_i64_i32 v[20:21], s[20:21], v19, s3, v[14:15]
	global_load_dwordx4 v[38:41], v[20:21], off
	s_or_b64 exec, exec, s[6:7]
	v_add_u32_e32 v19, 2, v17
	v_cmp_lt_u32_e32 vcc, v19, v18
	s_and_saveexec_b64 s[6:7], vcc
	v_mad_i64_i32 v[20:21], s[20:21], v16, s3, v[14:15]
	global_load_dwordx4 v[42:45], v[20:21], off
	s_or_b64 exec, exec, s[6:7]
	v_add_u32_e32 v19, 3, v17
	v_cmp_lt_u32_e32 vcc, v19, v18
	s_and_saveexec_b64 s[6:7], vcc
	v_add_u32_e32 v19, 1, v16
	v_mad_i64_i32 v[20:21], s[20:21], v19, s3, v[14:15]
	global_load_dwordx4 v[46:49], v[20:21], off
	s_or_b64 exec, exec, s[6:7]
	global_load_dwordx4 v[50:53], v[12:13], off
	global_load_dwordx4 v[54:57], v[12:13], off offset:16
	s_mov_b64 s[100:101], 0x1000
	v_lshl_add_u64 v[22:23], v[12:13], 0, s[100:101]
	global_load_dwordx4 v[58:61], v[22:23], off offset:1024
	global_load_dwordx4 v[62:65], v[22:23], off offset:1040
	s_mov_b64 s[100:101], 0x2000
	v_lshl_add_u64 v[22:23], v[12:13], 0, s[100:101]
	global_load_dwordx4 v[66:69], v[22:23], off offset:2048
	global_load_dwordx4 v[70:73], v[22:23], off offset:2064
	s_mov_b64 s[100:101], 0x3000
	v_lshl_add_u64 v[22:23], v[12:13], 0, s[100:101]
	global_load_dwordx4 v[74:77], v[22:23], off offset:3072
	global_load_dwordx4 v[78:81], v[22:23], off offset:3088
	s_waitcnt vmcnt(0)
	v_lshlrev_b32_e32 v82, 16, v34
	v_and_b32_e32 v83, 0xffff0000, v34
	v_pk_fma_f32 v[4:5], v[50:51], v[82:83], v[4:5]
	v_lshlrev_b32_e32 v82, 16, v35
	v_and_b32_e32 v83, 0xffff0000, v35
	v_pk_fma_f32 v[6:7], v[52:53], v[82:83], v[6:7]
	v_lshlrev_b32_e32 v82, 16, v36
	v_and_b32_e32 v83, 0xffff0000, v36
	v_pk_fma_f32 v[0:1], v[54:55], v[82:83], v[0:1]
	v_lshlrev_b32_e32 v82, 16, v37
	v_and_b32_e32 v83, 0xffff0000, v37
	v_pk_fma_f32 v[2:3], v[56:57], v[82:83], v[2:3]
	v_lshlrev_b32_e32 v82, 16, v38
	v_and_b32_e32 v83, 0xffff0000, v38
	v_pk_fma_f32 v[4:5], v[58:59], v[82:83], v[4:5]
	v_lshlrev_b32_e32 v82, 16, v39
	v_and_b32_e32 v83, 0xffff0000, v39
	v_pk_fma_f32 v[6:7], v[60:61], v[82:83], v[6:7]
	v_lshlrev_b32_e32 v82, 16, v40
	v_and_b32_e32 v83, 0xffff0000, v40
	v_pk_fma_f32 v[0:1], v[62:63], v[82:83], v[0:1]
	v_lshlrev_b32_e32 v82, 16, v41
	v_and_b32_e32 v83, 0xffff0000, v41
	v_pk_fma_f32 v[2:3], v[64:65], v[82:83], v[2:3]
	v_lshlrev_b32_e32 v82, 16, v42
	v_and_b32_e32 v83, 0xffff0000, v42
	v_pk_fma_f32 v[4:5], v[66:67], v[82:83], v[4:5]
	v_lshlrev_b32_e32 v82, 16, v43
	v_and_b32_e32 v83, 0xffff0000, v43
	v_pk_fma_f32 v[6:7], v[68:69], v[82:83], v[6:7]
	v_lshlrev_b32_e32 v82, 16, v44
	v_and_b32_e32 v83, 0xffff0000, v44
	v_pk_fma_f32 v[0:1], v[70:71], v[82:83], v[0:1]
	v_lshlrev_b32_e32 v82, 16, v45
	v_and_b32_e32 v83, 0xffff0000, v45
	v_pk_fma_f32 v[2:3], v[72:73], v[82:83], v[2:3]
	v_lshlrev_b32_e32 v82, 16, v46
	v_and_b32_e32 v83, 0xffff0000, v46
	v_pk_fma_f32 v[4:5], v[74:75], v[82:83], v[4:5]
	v_lshlrev_b32_e32 v82, 16, v47
	v_and_b32_e32 v83, 0xffff0000, v47
	v_pk_fma_f32 v[6:7], v[76:77], v[82:83], v[6:7]
	v_lshlrev_b32_e32 v82, 16, v48
	v_and_b32_e32 v83, 0xffff0000, v48
	v_pk_fma_f32 v[0:1], v[78:79], v[82:83], v[0:1]
	v_lshlrev_b32_e32 v82, 16, v49
	v_and_b32_e32 v83, 0xffff0000, v49
	v_pk_fma_f32 v[2:3], v[80:81], v[82:83], v[2:3]
	s_mov_b64 s[6:7], exec
	s_branch .LBB0_817
